# weight conversion: bf16 items converted (56 VALU) in the MFMA gaps of the next tile's O phase, only decode + 4 stores remain at the tile ends; fp8 items unchanged
# speedup vs baseline: 1.0008x; 1.0008x over previous
; #define LAS __attribute__((address_space(3)))
; #define RT_BAR() do { asm volatile("s_waitcnt lgkmcnt(0)" ::: "memory"); __builtin_amdgcn_s_barrier(); asm volatile("" ::: "memory"); } while (0)
; __device__ __forceinline__ void p2_ret(const Frame& F, ArgsP a, int layer) {
;     ...
;                   LAS unsigned char* pw = lds + RT_P + ((wr * 2 + wc) * 2) * 1024 + lane * 16;
;                   *(LAS u32x4*)pw = (u32x4){pk[0], pk[1], pk[2], pk[3]}; *(LAS u32x4*)(pw + 1024) = (u32x4){pk[4], pk[5], pk[6], pk[7]}; }
;                 RT_BAR();
;                 { bf16x8 pf[2][2];
.LBB0_387:
	s_cmp_eq_u32 s85, 1
	s_cbranch_scc1 .Lcvo_prep

; #define RT_BAR() do { asm volatile("s_waitcnt lgkmcnt(0)" ::: "memory"); __builtin_amdgcn_s_barrier(); asm volatile("" ::: "memory"); } while (0)
; __device__ __forceinline__ void p2_ret(const Frame& F, ArgsP a, int layer) {
;     ...
;                 asm volatile("s_waitcnt vmcnt(0)" ::: "memory");
;                 if (cv) { const CvU cu = cv_decode(a, F.ws, cvhi, layer); cv_store(cu, lane, cvv, cvsc); cvhi += cvs; }
;                 RT_BAR();
.Lcvo_join:
	s_add_i32 s12, s30, 0x80
	s_cmp_eq_u32 s12, s11
	s_cbranch_scc1 .Lrk_w0
	s_waitcnt vmcnt(4)
	s_branch .Lrk_wd

; __device__ __forceinline__ void p2_ret(const Frame& F, ArgsP a, int layer) {
;     ...
;                 const bool cv = cvhi < CV_HALF_ITEMS && ((cvtile++ & 1) == 0); f32x4 cvv[8], cvsc[2];
;                 if (cv) { const CvU cu = cv_decode(a, F.ws, cvhi, layer); cv_load(cu, lane, cvv, cvsc); }
;     ...
;                 if (cv) { const CvU cu = cv_decode(a, F.ws, cvhi, layer); cv_store(cu, lane, cvv, cvsc); cvhi += cvs; }
.Lrk_wd:
	s_and_b64 vcc, exec, s[38:39]
	s_cbranch_vccz .Lcvo_cvtile
	s_cmp_eq_u32 s85, 3
	s_cbranch_scc1 .Lcvo_st
	s_cmp_eq_u32 s85, 1
	s_cbranch_scc0 .LBB0_357
	s_mov_b32 s85, 0
	s_branch .Lcvo_storeblk
.Lcvo_cvtile:
	s_mov_b32 s85, 1
	s_add_i32 s12, s30, 0x80
	s_cmp_eq_u32 s12, s11
	s_cbranch_scc0 .LBB0_357
	s_mov_b32 s85, 0
.Lcvo_storeblk:
	v_mov_b32_e32 v0, v207
	s_ashr_i32 s14, s36, 1
	s_cmpk_lt_i32 s14, 0x400
	s_cselect_b64 s[4:5], -1, 0
	s_mov_b64 s[70:71], 0
	s_and_b64 vcc, exec, s[4:5]
	s_cbranch_vccnz .LBB0_394
	s_mov_b64 s[46:47], -1
	s_cmpk_gt_u32 s14, 0x13ff
	s_mov_b64 s[6:7], -1
	s_cbranch_scc0 .LBB0_391
	s_add_i32 s12, s14, 0xffffec00
	s_mov_b64 s[6:7], 0

; __device__ __forceinline__ unsigned cvt_pk_bf16(float lo, float hi) { unsigned r; asm volatile("v_cvt_pk_bf16_f32 %0, %1, %2" : "=v"(r) : "v"(lo), "v"(hi)); return r; }
; __device__ __forceinline__ void cv_store(const CvU& u, int lane, const f32x4 (&v)[8], const f32x4 (&sc)[2]) {
;     ...
; #pragma unroll
;     for (int c = 0; c < 4; ++c) { bf16_t* dst = u.WT + (size_t)(u.rowperm ? u.n0d + 64 * (nq >> 3) + ((4 * nq + c) & 31) : u.n0d + 4 * nq + c) * u.K + u.k0 + 8 * kq;
;         u32x4 o;
;         o.x = cvt_pk_bf16(v[0][c] * sc[0][0], v[1][c] * sc[0][1]); o.y = cvt_pk_bf16(v[2][c] * sc[0][2], v[3][c] * sc[0][3]);
;         o.z = cvt_pk_bf16(v[4][c] * sc[1][0], v[5][c] * sc[1][1]); o.w = cvt_pk_bf16(v[6][c] * sc[1][2], v[7][c] * sc[1][3]);
;         *(u32x4*)dst = o; }
.Lcvo_st:
	s_mov_b32 s85, 0
	global_store_dwordx4 v[228:229], v[198:201], off nt
	s_nop 0
	v_lshl_add_u64 v[228:229], v[228:229], 0, s[76:77]
	global_store_dwordx4 v[228:229], v[202:205], off nt
	s_nop 0
	v_lshl_add_u64 v[228:229], v[228:229], 0, s[76:77]
	global_store_dwordx4 v[228:229], v[212:215], off nt
	s_nop 0
	v_lshl_add_u64 v[228:229], v[228:229], 0, s[76:77]
	global_store_dwordx4 v[228:229], v[216:219], off nt
	s_branch .LBB0_356

; #define LAS __attribute__((address_space(3)))
; __device__ __forceinline__ void cv_store(const CvU& u, int lane, const f32x4 (&v)[8], const f32x4 (&sc)[2]) {
;     const int nq = lane & 15, kq = lane >> 4;
;     if (u.f8) {
; #pragma unroll
;         for (int c = 0; c < 4; ++c) { unsigned char* dst = (unsigned char*)u.WT + (size_t)(u.n0d + 4 * nq + c) * u.K + u.k0 + 8 * kq;
;             u32x2 o; o.x = pk4_fp8(v[0][c] * F8_SW, v[1][c] * F8_SW, v[2][c] * F8_SW, v[3][c] * F8_SW); o.y = pk4_fp8(v[4][c] * F8_SW, v[5][c] * F8_SW, v[6][c] * F8_SW, v[7][c] * F8_SW);
;             *(u32x2*)dst = o; }
;         return; }
; #pragma unroll
;     for (int c = 0; c < 4; ++c) { bf16_t* dst = u.WT + (size_t)(u.rowperm ? u.n0d + 64 * (nq >> 3) + ((4 * nq + c) & 31) : u.n0d + 4 * nq + c) * u.K + u.k0 + 8 * kq;
;         u32x4 o;
;         o.x = cvt_pk_bf16(v[0][c] * sc[0][0], v[1][c] * sc[0][1]); o.y = cvt_pk_bf16(v[2][c] * sc[0][2], v[3][c] * sc[0][3]);
;         o.z = cvt_pk_bf16(v[4][c] * sc[1][0], v[5][c] * sc[1][1]); o.w = cvt_pk_bf16(v[6][c] * sc[1][2], v[7][c] * sc[1][3]);
;         *(u32x4*)dst = o; }
; __device__ __forceinline__ void p2_ret(const Frame& F, ArgsP a, int layer) {
;     ...
;                 { bf16x8 pf[2][2];
; #pragma unroll
;                   for (int kb2 = 0; kb2 < 2; ++kb2)
; #pragma unroll
;                       for (int s = 0; s < 2; ++s) pf[kb2][s] = *(const LAS bf16x8*)(lds + RT_P + ((wr * 2 + kb2) * 2 + s) * 1024 + lane * 16);
;                   const LAS unsigned char* vb = lds + RT_V0 + bf * 32768 + (128 * wc + kap) * 128;
;     ...
;                   bf16x8 va[2], vc[2];
;                   RT_VRD(va, 0); __builtin_amdgcn_sched_barrier(0);
;                   RT_VRD(vc, 1); RT_VMM(va, 0); __builtin_amdgcn_sched_barrier(0);
;                   RT_VRD(va, 2); RT_VMM(vc, 1); __builtin_amdgcn_sched_barrier(0);
;                   RT_VRD(vc, 3); RT_VMM(va, 2); __builtin_amdgcn_sched_barrier(0);
;                   RT_VRD(va, 4); RT_VMM(vc, 3); __builtin_amdgcn_sched_barrier(0);
;                   RT_VRD(vc, 5); RT_VMM(va, 4); __builtin_amdgcn_sched_barrier(0);
;                   RT_VRD(va, 6); RT_VMM(vc, 5); __builtin_amdgcn_sched_barrier(0);
;                   RT_VRD(vc, 7); RT_VMM(va, 6); __builtin_amdgcn_sched_barrier(0);
;                   RT_VMM(vc, 7); __builtin_amdgcn_sched_barrier(0);
.Lcvo_406:
	s_lshl_b32 s14, s15, 6
	s_lshl_b32 s15, s36, 5
	v_and_b32_e32 v100, 15, v0
	v_ashrrev_i32_e32 v0, 4, v0
	s_and_b32 s15, s15, 32
	v_lshlrev_b32_e32 v98, 3, v0
	s_or_b32 s70, s14, s15
	s_and_b64 vcc, exec, s[38:39]
	v_ashrrev_i32_e32 v99, 31, v98
	s_cbranch_vccnz .Lcvo_408
	s_branch .Lcvo_fp8
.Lcvo_408:
	s_andn2_b64 vcc, exec, s[6:7]
	s_cbranch_vccnz .Lcvo_fp8
	v_lshlrev_b32_e32 v0, 3, v100
	v_lshlrev_b32_e32 v100, 2, v100
	v_and_b32_e32 v101, 28, v100
	v_and_or_b32 v0, v0, 64, v101
	v_cndmask_b32_e64 v0, v0, v100, s[46:47]
	v_add_u32_e32 v0, s13, v0
	v_mad_i64_i32 v[100:101], s[6:7], s12, v0, 0
	s_ashr_i32 s71, s70, 31
	v_lshl_add_u64 v[100:101], v[100:101], 1, s[4:5]
	s_lshl_b64 s[6:7], s[70:71], 1
	v_lshl_add_u64 v[100:101], v[100:101], 0, s[6:7]
	v_lshlrev_b64 v[102:103], 1, v[98:99]
	v_lshl_add_u64 v[228:229], v[100:101], 0, v[102:103]
	s_lshl_b32 s76, s12, 1
	s_mov_b32 s77, 0
	s_mov_b32 s85, 3
	v_mov_b32_e32 v0, v207
	s_and_b32 s6, s31, 0x8000
	s_mov_b64 s[38:39], -1
	s_branch .Lcvo_O
.Lcvo_fp8:
	v_mov_b32_e32 v0, v207
	s_and_b32 s6, s31, 0x8000
	s_mov_b64 s[38:39], -1
	s_branch .Lcvo_back
.Lcvo_O:
	s_nop 6
	v_lshlrev_b32_e32 v98, 4, v0
	v_add_u32_e32 v99, s83, v98
	ds_write_b128 v99, v[190:193]
	ds_write_b128 v99, v[194:197] offset:1024
	s_lshl_b32 s12, s80, 6
	s_sub_i32 s12, 0x800, s12
	s_add_i32 s12, s12, s82
	v_add_u32_e32 v250, s12, v98
	ds_read_b128 v[242:245], v246 offset:4096
	ds_read_b128 v[106:109], v247 offset:4096
	s_waitcnt lgkmcnt(5)
	v_mfma_f32_32x32x16_bf16 v[82:97], v[234:237], v[190:193], v[82:97]
	v_mul_f32_e32 v230, v186, v2
	v_mul_f32_e32 v231, v187, v6
	v_cvt_pk_bf16_f32 v198, v230, v231
	s_waitcnt lgkmcnt(4)
	v_mfma_f32_32x32x16_bf16 v[82:97], v[238:241], v[194:197], v[82:97]
	v_mul_f32_e32 v230, v188, v10
	v_mul_f32_e32 v231, v189, v14
	v_cvt_pk_bf16_f32 v199, v230, v231
	ds_read_b128 v[234:237], v246 offset:8192
	ds_read_b128 v[238:241], v247 offset:8192
	s_waitcnt lgkmcnt(3)
	v_mfma_f32_32x32x16_bf16 v[66:81], v[242:245], v[190:193], v[66:81]
	v_mul_f32_e32 v230, v182, v18
	v_mul_f32_e32 v231, v183, v22
	v_cvt_pk_bf16_f32 v200, v230, v231
	s_waitcnt lgkmcnt(2)
	v_mfma_f32_32x32x16_bf16 v[66:81], v[106:109], v[194:197], v[66:81]
	v_mul_f32_e32 v230, v184, v26
	v_mul_f32_e32 v231, v185, v30
	v_cvt_pk_bf16_f32 v201, v230, v231
	ds_read_b128 v[242:245], v246 offset:12288
	ds_read_b128 v[106:109], v247 offset:12288
	s_waitcnt lgkmcnt(3)
	v_mfma_f32_32x32x16_bf16 v[50:65], v[234:237], v[190:193], v[50:65]
	v_mul_f32_e32 v230, v186, v3
	v_mul_f32_e32 v231, v187, v7
	v_cvt_pk_bf16_f32 v202, v230, v231
	s_waitcnt lgkmcnt(2)
	v_mfma_f32_32x32x16_bf16 v[50:65], v[238:241], v[194:197], v[50:65]
	v_mul_f32_e32 v230, v188, v11
	v_mul_f32_e32 v231, v189, v15
	v_cvt_pk_bf16_f32 v203, v230, v231
	ds_read_b128 v[234:237], v248
	ds_read_b128 v[238:241], v249
	s_barrier
	ds_read_b128 v[98:101], v250
	ds_read_b128 v[102:105], v250 offset:1024
	s_add_i32 s12, s30, 0x80
	s_cmp_eq_u32 s12, s11
	s_cbranch_scc1 .Lcvo_skip
	s_add_i32 s13, s22, s6
	s_mov_b32 m0, s13
	s_add_i32 s12, s27, 0x10000
	buffer_load_dwordx4 v224, s[40:43], s12 offen lds
	s_add_i32 m0, s13, 0x2000
	s_add_i32 s12, s27, 0x20000
	buffer_load_dwordx4 v224, s[40:43], s12 offen lds
	s_add_i32 m0, s13, 0x4000
	s_add_i32 s12, s27, 0x30000
	buffer_load_dwordx4 v224, s[40:43], s12 offen lds
	s_add_i32 m0, s13, 0x6000
	s_add_i32 s12, s27, 0x40000
	buffer_load_dwordx4 v224, s[40:43], s12 offen lds
.Lcvo_skip:
	s_waitcnt lgkmcnt(5)
	v_mfma_f32_32x32x16_bf16 v[34:49], v[242:245], v[190:193], v[34:49]
	v_mul_f32_e32 v230, v182, v19
	v_mul_f32_e32 v231, v183, v23
	v_cvt_pk_bf16_f32 v204, v230, v231
	s_waitcnt lgkmcnt(4)
	v_mfma_f32_32x32x16_bf16 v[34:49], v[106:109], v[194:197], v[34:49]
	v_mul_f32_e32 v230, v184, v27
	v_mul_f32_e32 v231, v185, v31
	v_cvt_pk_bf16_f32 v205, v230, v231
	ds_read_b128 v[242:245], v248 offset:4096
	ds_read_b128 v[106:109], v249 offset:4096
	s_waitcnt lgkmcnt(2)
	v_mfma_f32_32x32x16_bf16 v[82:97], v[234:237], v[98:101], v[82:97]
	v_mul_f32_e32 v230, v186, v4
	v_mul_f32_e32 v231, v187, v8
	v_cvt_pk_bf16_f32 v212, v230, v231
	v_mfma_f32_32x32x16_bf16 v[82:97], v[238:241], v[102:105], v[82:97]
	v_mul_f32_e32 v230, v188, v12
	v_mul_f32_e32 v231, v189, v16
	v_cvt_pk_bf16_f32 v213, v230, v231
	ds_read_b128 v[234:237], v248 offset:8192
	ds_read_b128 v[238:241], v249 offset:8192
	s_waitcnt lgkmcnt(3)
	v_mfma_f32_32x32x16_bf16 v[66:81], v[242:245], v[98:101], v[66:81]
	v_mul_f32_e32 v230, v182, v20
	v_mul_f32_e32 v231, v183, v24
	v_cvt_pk_bf16_f32 v214, v230, v231
	s_waitcnt lgkmcnt(2)
	v_mfma_f32_32x32x16_bf16 v[66:81], v[106:109], v[102:105], v[66:81]
	v_mul_f32_e32 v230, v184, v28
	v_mul_f32_e32 v231, v185, v32
	v_cvt_pk_bf16_f32 v215, v230, v231
	ds_read_b128 v[242:245], v248 offset:12288
	ds_read_b128 v[106:109], v249 offset:12288
	s_waitcnt lgkmcnt(3)
	v_mfma_f32_32x32x16_bf16 v[50:65], v[234:237], v[98:101], v[50:65]
	v_mul_f32_e32 v230, v186, v5
	v_mul_f32_e32 v231, v187, v9
	v_cvt_pk_bf16_f32 v216, v230, v231
	s_waitcnt lgkmcnt(2)
	v_mfma_f32_32x32x16_bf16 v[50:65], v[238:241], v[102:105], v[50:65]
	v_mul_f32_e32 v230, v188, v13
	v_mul_f32_e32 v231, v189, v17
	v_cvt_pk_bf16_f32 v217, v230, v231
	s_waitcnt lgkmcnt(1)
	v_mfma_f32_32x32x16_bf16 v[34:49], v[242:245], v[98:101], v[34:49]
	v_mul_f32_e32 v230, v182, v21
	v_mul_f32_e32 v231, v183, v25
	v_cvt_pk_bf16_f32 v218, v230, v231
	s_waitcnt lgkmcnt(0)
	v_mfma_f32_32x32x16_bf16 v[34:49], v[106:109], v[102:105], v[34:49]
	v_mul_f32_e32 v230, v184, v29
	v_mul_f32_e32 v231, v185, v33
	v_cvt_pk_bf16_f32 v219, v230, v231
	s_branch .Lcvo_join
